# SEL prologue: removed the vmcnt(0) that serialized gate/mask/OCMP loads ahead of the Q loads
# speedup vs baseline: 1.0040x; 1.0040x over previous
; template <int DQK, int MODE> ...
;     ...
;     const int tid = fresh_tid2(wv0), lane = tid & 63, wid = wv0, r32 = lane & 31, hi = lane >> 5;
;     const int qpos = q0 + 32 * wid + r32, qmin = q0 + 32 * wid, qmax = qmin + 31;
;     bf16x8 qf[NKS];
; #pragma unroll
;     for (int ks = 0; ks < NKS; ++ks) qf[ks] = *(const bf16x8*)(Qp + (size_t)(32 * wid + r32) * qpitch + 16 * ks + 8 * hi);
;     if (DQK == 96) {
; #pragma unroll
;         for (int ks = 4; ks < NKS; ++ks) {
;             const int p0 = 8 * (ks - 4) + 4 * hi;
;             const f32x4 c4 = *(const f32x4*)(rope + ROPE_MLA_COS + qpos * 16 + p0), s4 = *(const f32x4*)(rope + ROPE_MLA_SIN + qpos * 16 + p0);
;             u32x4 w = __builtin_bit_cast(u32x4, qf[ks]);
; #pragma unroll
;             for (int k = 0; k < 4; ++k) { const float x1 = bflo(w[k]), x2 = bfhi(w[k]); w[k] = cvtpk(x1 * c4[k] - x2 * s4[k], x2 * c4[k] + x1 * s4[k]); }
;             qf[ks] = __builtin_bit_cast(bf16x8, w);
;         }
;     }
; #pragma unroll
;     for (int ks = 0; ks < NKS; ++ks) asm volatile("" : "+v"(qf[ks]));
;     f32x16 o[2]; o[0] = (f32x16){}; o[1] = (f32x16){};
;     float mref = -1e30f, l = 0.f;
;     const int srow = tid >> 3, sch = tid & 7, srow2 = tid >> 2, sch2 = tid & 3;
;     u32x4 rk1, rk2 = (u32x4){}, rv;
;     ...
;     FL_GLOAD(t0);
; __global__ void __launch_bounds__(512) mega_fwd(Params P) {
;     ...
;                     const float g1 = GATES[qrow * 32 + h * 3 + 1], g2 = GATES[qrow * 32 + h * 3 + 2];
;                     const u32x4 mw = *(const u32x4*)(MASKS + ((size_t)(b * 2 + g) * SEQ + q0 + 32 * wid + r32) * 4);
;                     f32x16 tot[2];
;                     { const bf16_t* oc = OCMP + qrow * 384 + h * 64;
; #pragma unroll
;                       for (int d0 = 0; d0 < 2; ++d0)
; #pragma unroll
;                           for (int j = 0; j < 4; ++j) { const u32x2 w = *(const u32x2*)(oc + 32 * d0 + 8 * j + 4 * hi); tot[d0][4 * j] = bflo(w.x); tot[d0][4 * j + 1] = bfhi(w.x); tot[d0][4 * j + 2] = bflo(w.y); tot[d0][4 * j + 3] = bfhi(w.y); } }
;                     const bf16_t* Qp = PROJ + (rb + q0) * NPROJ + PC_NQ + 64 * h;
;                     flash_unit<64, MODE_SEL>(lds, wv0, Qp, NPROJ, PROJ + rb * NPROJ + PC_KS + 64 * g, NPROJ, nullptr, 0, PROJ + rb * NPROJ + PC_VS + 64 * g, NPROJ,
;                                              q0, 0, (q0 + 256) / 64, 0.125f * LOG2E, mw, g1, tot, nullptr);
.LBB0_1306:
	s_or_b64 exec, exec, s[0:1]
	v_mov_b32_e32 v0, s38
	s_waitcnt lgkmcnt(0)
	s_barrier
	ds_read_b32 v0, v0
	s_movk_i32 s0, 0x3ff
	s_waitcnt lgkmcnt(0)
	v_cmp_lt_i32_e32 vcc, s0, v0
	v_readfirstlane_b32 s34, v0
	s_mov_b64 s[0:1], -1
	s_cbranch_vccnz .LBB0_1303
	s_cmpk_lt_i32 s34, 0x300
	s_cbranch_scc0 .LBB0_1372
	s_mul_hi_i32 s0, s34, 0xd5555555
	s_lshr_b32 s1, s0, 31
	s_lshr_b32 s0, s0, 2
	s_add_i32 s4, s0, s1
	s_mul_hi_i32 s0, s34, 0x2aaaaaab
	s_lshr_b32 s1, s0, 31
	s_lshr_b32 s0, s0, 2
	s_add_i32 s0, s0, s1
	s_mul_i32 s0, s0, 24
	s_sub_i32 s6, s34, s0
	s_mul_i32 s0, s6, 43
	s_sext_i32_i16 s1, s0
	s_lshr_b32 s1, s1, 9
	s_bfe_u32 s0, s0, 0x1000f
	s_add_i32 s0, s1, s0
	s_mul_i32 s0, s0, 12
	s_sub_i32 s1, s6, s0
	s_bfe_i32 s0, s1, 0x80000
	s_mul_i32 s0, s0, 43
	s_bfe_u32 s5, s0, 0x1000f
	s_bfe_u32 s0, s0, 0x80008
	s_add_i32 s0, s0, s5
	s_mul_i32 s5, s0, 6
	s_sub_i32 s1, s1, s5
	s_lshl_b32 s35, s4, 8
	s_bfe_i64 s[8:9], s[0:1], 0x80000
	s_add_i32 s36, s35, 0x1f00
	s_lshl_b64 s[4:5], s[8:9], 13
	s_add_u32 s26, s4, s36
	s_addc_u32 s27, s5, 0
	s_sext_i32_i8 s37, s1
	v_lshl_add_u64 v[180:181], s[26:27], 0, v[174:175]
	s_mov_b64 s[4:5], -1
	s_cmp_gt_i32 s6, 11
	s_mul_hi_i32 s45, s8, 0x2800000
	s_mul_i32 s46, s8, 0x2800000
	s_cbranch_scc0 .LBB0_1346
	s_bfe_i32 s1, s1, 0x80000
	s_mulk_i32 s1, 0x56
	s_bfe_u32 s4, s1, 0x1000f
	s_bfe_u32 s1, s1, 0x80008
	s_add_i32 s1, s1, s4
	s_sext_i32_i8 s6, s1
	s_sext_i32_i8 s0, s0
	s_lshl_b32 s0, s0, 14
	s_lshl_b32 s1, s6, 13
	s_add_i32 s1, s1, s0
	s_add_u32 s0, s1, s36
	s_addc_u32 s1, 0, 0
	v_mov_b64_e32 v[6:7], s[18:19]
	v_lshl_add_u64 v[4:5], s[0:1], 0, v[174:175]
	v_mad_u64_u32 v[6:7], s[0:1], v180, s72, v[6:7]
	v_mov_b32_e32 v0, v7
	v_lshlrev_b64 v[2:3], 7, v[180:181]
	v_mad_u64_u32 v[8:9], s[0:1], v181, s72, v[0:1]
	s_mul_i32 s80, s37, 3
	v_lshl_add_u64 v[2:3], s[14:15], 0, v[2:3]
	s_mul_i32 s0, s27, 0x1400
	s_mul_hi_u32 s1, s26, 0x1400
	v_lshl_add_u64 v[2:3], s[80:81], 2, v[2:3]
	s_lshl_b32 s9, s37, 6
	s_lshl_b32 s80, s37, 7
	s_add_i32 s1, s1, s0
	s_mul_i32 s0, s26, 0x1400
	s_add_u32 s0, s39, s0
	v_mov_b32_e32 v7, v8
	s_addc_u32 s1, s40, s1
	v_lshl_add_u64 v[6:7], v[6:7], 0, s[80:81]
	v_mov_b32_e32 v179, v1
	s_add_u32 s30, s0, s80
	v_lshl_add_u64 v[4:5], v[4:5], 4, s[16:17]
	v_lshl_add_u64 v[6:7], v[6:7], 0, v[178:179]
	s_addc_u32 s31, s1, 0
	s_mov_b32 s1, s81
	v_mov_b32_e32 v0, v1
	flat_load_dwordx2 v[182:183], v[2:3] offset:4
	s_nop 0
	flat_load_dwordx4 v[2:5], v[4:5]
	s_nop 0
	flat_load_dwordx2 v[198:199], v[6:7]
	flat_load_dwordx2 v[196:197], v[6:7] offset:16
	flat_load_dwordx2 v[194:195], v[6:7] offset:32
	flat_load_dwordx2 v[192:193], v[6:7] offset:48
	flat_load_dwordx2 v[190:191], v[6:7] offset:64
	flat_load_dwordx2 v[188:189], v[6:7] offset:80
	flat_load_dwordx2 v[186:187], v[6:7] offset:96
	flat_load_dwordx2 v[184:185], v[6:7] offset:112
	v_readlane_b32 s7, v254, 6
	v_mbcnt_lo_u32_b32 v0, -1, v0
	v_mbcnt_hi_u32_b32 v26, -1, v0
	v_and_b32_e32 v27, 31, v26
	v_bfe_u32 v28, v26, 5, 1
	v_or_b32_e32 v0, s7, v27
	v_mov_b64_e32 v[6:7], s[30:31]
	v_mad_i64_i32 v[6:7], s[4:5], v0, s69, v[6:7]
	v_lshlrev_b32_e32 v0, 4, v28
	v_lshl_add_u64 v[6:7], v[6:7], 0, v[0:1]
	flat_load_dwordx4 v[84:87], v[6:7] offset:832
	flat_load_dwordx4 v[80:83], v[6:7] offset:864
	flat_load_dwordx4 v[10:13], v[6:7] offset:896
	s_nop 0
	flat_load_dwordx4 v[6:9], v[6:7] offset:928
	s_add_u32 s0, s39, s46
	v_or_b32_e32 v14, s79, v26
	s_addc_u32 s4, s40, s45
	s_lshl_b32 s5, s6, 7
	v_and_b32_e32 v15, 7, v26
	v_ashrrev_i32_e32 v24, 3, v14
	s_add_u32 s28, s0, s5
	v_lshlrev_b32_e32 v29, 4, v15
	v_mul_lo_u32 v14, v24, s69
	v_mov_b32_e32 v23, v1
	s_addc_u32 s29, s4, 0
	v_or_b32_e32 v22, v29, v14
	v_lshl_add_u64 v[18:19], s[28:29], 0, v[22:23]
	s_movk_i32 s4, 0x90
	v_mul_lo_u32 v23, v24, s4
	v_mov_b32_e32 v25, v1
	v_add3_u32 v129, s1, v23, v29
	v_add_u32_e32 v24, 0x50000, v22
	v_lshl_add_u64 v[24:25], s[28:29], 0, v[24:25]
	v_add_u32_e32 v226, 0xa0000, v22
	v_mov_b32_e32 v227, v1
	v_lshl_add_u64 v[226:227], s[28:29], 0, v[226:227]
	v_add_u32_e32 v232, 0xf0000, v22
	v_mov_b32_e32 v233, v1
	v_lshl_add_u64 v[232:233], s[28:29], 0, v[232:233]
	v_mad_u32_u24 v131, v27, s4, v0
	v_lshlrev_b32_e32 v128, 2, v28
	v_lshrrev_b32_e32 v0, 2, v26
	s_add_i32 s0, s35, 0x2000
	s_add_i32 s48, s36, s7
	v_and_or_b32 v0, v0, 3, v128
	v_mov_b32_e32 v30, v1
	v_mov_b32_e32 v31, v1
	s_lshr_b32 s47, s0, 6
	v_mov_b32_e32 v23, v1
	v_mov_b32_e32 v28, v1
	v_mov_b32_e32 v29, v1
	s_mov_b32 s53, s81
	s_mov_b32 s50, 0
	s_or_b32 s49, s48, 31
	s_add_i32 s0, s47, -1
	v_mov_b32_e32 v179, 0
	s_mov_b32 s51, 63
	global_load_dwordx4 v[14:17], v[18:19], off offset:2112
	s_nop 0
	global_load_dwordx4 v[18:21], v[18:19], off offset:2368
	global_load_dwordx4 v[88:91], v[24:25], off offset:2368
	global_load_dwordx4 v[92:95], v[24:25], off offset:2112
	s_waitcnt vmcnt(0) lgkmcnt(0)
	s_waitcnt lgkmcnt(0)
	s_barrier
	s_waitcnt vmcnt(0)
	ds_write_b128 v129, v[14:17]
	ds_write_b128 v129, v[18:21] offset:36864
	v_add_u32_e32 v229, 0x2400, v129
	ds_write_b128 v229, v[92:95]
	ds_write_b128 v229, v[88:91] offset:36864
	global_load_dwordx4 v[88:91], v[226:227], off offset:2368
	global_load_dwordx4 v[92:95], v[226:227], off offset:2112
	global_load_dwordx4 v[222:225], v[232:233], off offset:2368
	global_load_dwordx4 v[218:221], v[232:233], off offset:2112
	v_lshlrev_b32_e32 v14, 1, v26
	v_and_b32_e32 v14, 32, v14
	v_lshlrev_b32_e32 v16, 3, v26
	v_and_or_b32 v14, v16, 24, v14
	v_or_b32_e32 v15, s48, v27
	v_mad_u32_u24 v130, v0, s4, v14
	v_add_u32_e32 v0, 0xf0000, v22
	v_mov_b32_e32 v16, v1
	v_mov_b32_e32 v17, v1
	v_mov_b32_e32 v18, v1
	v_mov_b32_e32 v19, v1
	v_mov_b32_e32 v20, v1
	v_mov_b32_e32 v21, v1
	v_mov_b32_e32 v22, v1
	v_mov_b32_e32 v24, v1
	v_mov_b32_e32 v25, v1
	v_mov_b32_e32 v26, v1
	v_mov_b32_e32 v27, v1
	v_mov_b64_e32 v[46:47], v[30:31]
	v_mov_b32_e32 v14, 0xf149f2ca
	v_mov_b64_e32 v[44:45], v[28:29]
	v_mov_b64_e32 v[42:43], v[26:27]
	v_mov_b64_e32 v[40:41], v[24:25]
	v_mov_b64_e32 v[38:39], v[22:23]
	v_mov_b64_e32 v[36:37], v[20:21]
	v_mov_b64_e32 v[34:35], v[18:19]
	v_mov_b64_e32 v[32:33], v[16:17]
	s_waitcnt lgkmcnt(0)
	s_barrier
	s_branch .LBB0_1311
